# merge K-loop: hoist per-iteration vmcnt(0) to preheader
# speedup vs baseline: 1.0071x; 1.0071x over previous
.LBB0_43:
	s_add_u32 s16, s6, 0x100
	v_readlane_b32 s14, v252, 51
	s_addc_u32 s17, s7, 0
	v_add_u32_e32 v3, s62, v2
	v_add_u32_e32 v132, s14, v2
	s_add_u32 s4, s4, 0x40080
	v_mov_b32_e32 v2, 0
	v_mov_b32_e32 v131, v1
	s_addc_u32 s5, s5, 0
	s_mov_b32 s29, -2
	v_add_u32_e32 v133, 0, v3
	v_mov_b32_e32 v3, v2
	v_mov_b32_e32 v4, v2
	v_mov_b32_e32 v5, v2
	v_mov_b32_e32 v6, v2
	v_mov_b32_e32 v7, v2
	v_mov_b32_e32 v8, v2
	v_mov_b32_e32 v9, v2
	v_mov_b32_e32 v18, v2
	v_mov_b32_e32 v19, v2
	v_mov_b32_e32 v20, v2
	v_mov_b32_e32 v21, v2
	v_mov_b32_e32 v22, v2
	v_mov_b32_e32 v23, v2
	v_mov_b32_e32 v24, v2
	v_mov_b32_e32 v25, v2
	v_mov_b32_e32 v34, v2
	v_mov_b32_e32 v35, v2
	v_mov_b32_e32 v36, v2
	v_mov_b32_e32 v37, v2
	v_mov_b32_e32 v38, v2
	v_mov_b32_e32 v39, v2
	v_mov_b32_e32 v40, v2
	v_mov_b32_e32 v41, v2
	v_mov_b32_e32 v50, v2
	v_mov_b32_e32 v51, v2
	v_mov_b32_e32 v52, v2
	v_mov_b32_e32 v53, v2
	v_mov_b32_e32 v54, v2
	v_mov_b32_e32 v55, v2
	v_mov_b32_e32 v56, v2
	v_mov_b32_e32 v57, v2
	v_mov_b32_e32 v10, v2
	v_mov_b32_e32 v11, v2
	v_mov_b32_e32 v12, v2
	v_mov_b32_e32 v13, v2
	v_mov_b32_e32 v14, v2
	v_mov_b32_e32 v15, v2
	v_mov_b32_e32 v16, v2
	v_mov_b32_e32 v17, v2
	v_mov_b32_e32 v26, v2
	v_mov_b32_e32 v27, v2
	v_mov_b32_e32 v28, v2
	v_mov_b32_e32 v29, v2
	v_mov_b32_e32 v30, v2
	v_mov_b32_e32 v31, v2
	v_mov_b32_e32 v32, v2
	v_mov_b32_e32 v33, v2
	v_mov_b32_e32 v42, v2
	v_mov_b32_e32 v43, v2
	v_mov_b32_e32 v44, v2
	v_mov_b32_e32 v45, v2
	v_mov_b32_e32 v46, v2
	v_mov_b32_e32 v47, v2
	v_mov_b32_e32 v48, v2
	v_mov_b32_e32 v49, v2
	v_mov_b32_e32 v58, v2
	v_mov_b32_e32 v59, v2
	v_mov_b32_e32 v60, v2
	v_mov_b32_e32 v61, v2
	v_mov_b32_e32 v62, v2
	v_mov_b32_e32 v63, v2
	v_mov_b32_e32 v64, v2
	v_mov_b32_e32 v65, v2
	v_mov_b32_e32 v66, v2
	v_mov_b32_e32 v67, v2
	v_mov_b32_e32 v68, v2
	v_mov_b32_e32 v69, v2
	v_mov_b32_e32 v70, v2
	v_mov_b32_e32 v71, v2
	v_mov_b32_e32 v72, v2
	v_mov_b32_e32 v73, v2
	v_mov_b32_e32 v82, v2
	v_mov_b32_e32 v83, v2
	v_mov_b32_e32 v84, v2
	v_mov_b32_e32 v85, v2
	v_mov_b32_e32 v86, v2
	v_mov_b32_e32 v87, v2
	v_mov_b32_e32 v88, v2
	v_mov_b32_e32 v89, v2
	v_mov_b32_e32 v98, v2
	v_mov_b32_e32 v99, v2
	v_mov_b32_e32 v100, v2
	v_mov_b32_e32 v101, v2
	v_mov_b32_e32 v102, v2
	v_mov_b32_e32 v103, v2
	v_mov_b32_e32 v104, v2
	v_mov_b32_e32 v105, v2
	v_mov_b32_e32 v114, v2
	v_mov_b32_e32 v115, v2
	v_mov_b32_e32 v116, v2
	v_mov_b32_e32 v117, v2
	v_mov_b32_e32 v118, v2
	v_mov_b32_e32 v119, v2
	v_mov_b32_e32 v120, v2
	v_mov_b32_e32 v121, v2
	v_mov_b32_e32 v74, v2
	v_mov_b32_e32 v75, v2
	v_mov_b32_e32 v76, v2
	v_mov_b32_e32 v77, v2
	v_mov_b32_e32 v78, v2
	v_mov_b32_e32 v79, v2
	v_mov_b32_e32 v80, v2
	v_mov_b32_e32 v81, v2
	v_mov_b32_e32 v90, v2
	v_mov_b32_e32 v91, v2
	v_mov_b32_e32 v92, v2
	v_mov_b32_e32 v93, v2
	v_mov_b32_e32 v94, v2
	v_mov_b32_e32 v95, v2
	v_mov_b32_e32 v96, v2
	v_mov_b32_e32 v97, v2
	v_mov_b32_e32 v106, v2
	v_mov_b32_e32 v107, v2
	v_mov_b32_e32 v108, v2
	v_mov_b32_e32 v109, v2
	v_mov_b32_e32 v110, v2
	v_mov_b32_e32 v111, v2
	v_mov_b32_e32 v112, v2
	v_mov_b32_e32 v113, v2
	v_mov_b32_e32 v122, v2
	v_mov_b32_e32 v123, v2
	v_mov_b32_e32 v124, v2
	v_mov_b32_e32 v125, v2
	v_mov_b32_e32 v126, v2
	v_mov_b32_e32 v127, v2
	v_mov_b32_e32 v128, v2
	v_mov_b32_e32 v129, v2
	s_waitcnt vmcnt(0)
.LBB0_44:
	s_add_u32 s6, s4, 0xfffc0080
	s_addc_u32 s7, s5, -1
	s_add_i32 s30, 0, 0x10000
	v_add_u32_e32 v146, s30, v132
	ds_read_b128 v[134:137], v146
	ds_read_b128 v[138:141], v146 offset:1024
	ds_read_b128 v[142:145], v146 offset:2048
	ds_read_b128 v[146:149], v146 offset:3072
	s_cmp_eq_u32 s29, 12
	s_cselect_b32 s15, s9, s7
	s_cselect_b32 s14, s8, s6
	s_cselect_b32 s7, s11, s17
	s_cselect_b32 s6, s10, s16
	v_lshl_add_u64 v[182:183], s[4:5], 0, v[0:1]
	s_add_i32 m0, s63, 0xc000
	ds_read_b128 v[150:153], v133
	ds_read_b128 v[154:157], v133 offset:1024
	ds_read_b128 v[158:161], v133 offset:2048
	ds_read_b128 v[162:165], v133 offset:3072
	ds_read_b128 v[166:169], v133 offset:4096
	ds_read_b128 v[170:173], v133 offset:5120
	ds_read_b128 v[174:177], v133 offset:6144
	ds_read_b128 v[178:181], v133 offset:7168
	global_load_lds_dwordx4 v[182:183], off
	v_lshl_add_u64 v[182:183], s[4:5], 0, v[130:131]
	s_add_i32 m0, s63, 0xe000
	s_nop 0
	global_load_lds_dwordx4 v[182:183], off
	s_waitcnt lgkmcnt(8)
	s_barrier
	s_waitcnt lgkmcnt(0)
	s_setprio 1
	s_waitcnt lgkmcnt(0)
	v_mfma_f32_16x16x32_bf16 v[126:129], v[134:137], v[150:153], v[126:129]
	v_mfma_f32_16x16x32_bf16 v[122:125], v[142:145], v[150:153], v[122:125]
	v_mfma_f32_16x16x32_bf16 v[110:113], v[134:137], v[158:161], v[110:113]
	v_mfma_f32_16x16x32_bf16 v[106:109], v[142:145], v[158:161], v[106:109]
	v_mfma_f32_16x16x32_bf16 v[94:97], v[134:137], v[166:169], v[94:97]
	v_mfma_f32_16x16x32_bf16 v[90:93], v[142:145], v[166:169], v[90:93]
	v_mfma_f32_16x16x32_bf16 v[78:81], v[134:137], v[174:177], v[78:81]
	v_mfma_f32_16x16x32_bf16 v[74:77], v[142:145], v[174:177], v[74:77]
	v_mfma_f32_16x16x32_bf16 v[126:129], v[138:141], v[154:157], v[126:129]
	v_mfma_f32_16x16x32_bf16 v[122:125], v[146:149], v[154:157], v[122:125]
	v_mfma_f32_16x16x32_bf16 v[110:113], v[138:141], v[162:165], v[110:113]
	v_mfma_f32_16x16x32_bf16 v[106:109], v[146:149], v[162:165], v[106:109]
	v_mfma_f32_16x16x32_bf16 v[94:97], v[138:141], v[170:173], v[94:97]
	v_mfma_f32_16x16x32_bf16 v[90:93], v[146:149], v[170:173], v[90:93]
	v_mfma_f32_16x16x32_bf16 v[78:81], v[138:141], v[178:181], v[78:81]
	v_mfma_f32_16x16x32_bf16 v[74:77], v[146:149], v[178:181], v[74:77]
	s_setprio 0
	s_barrier
	s_add_i32 s36, 0, 0x14000
	v_add_u32_e32 v190, s36, v132
	s_add_i32 s30, s30, s53
	ds_read_b128 v[182:185], v190
	ds_read_b128 v[186:189], v190 offset:1024
	ds_read_b128 v[192:195], v190 offset:2048
	ds_read_b128 v[196:199], v190 offset:3072
	v_lshl_add_u64 v[190:191], s[6:7], 0, v[0:1]
	s_mov_b32 m0, s30
	v_lshl_add_u64 v[200:201], s[6:7], 0, v[130:131]
	global_load_lds_dwordx4 v[190:191], off
	s_add_i32 m0, s30, 0x2000
	s_nop 0
	global_load_lds_dwordx4 v[200:201], off
	s_barrier
	s_waitcnt lgkmcnt(0)
	s_setprio 1
	s_waitcnt lgkmcnt(0)
	v_mfma_f32_16x16x32_bf16 v[118:121], v[182:185], v[150:153], v[118:121]
	v_mfma_f32_16x16x32_bf16 v[114:117], v[192:195], v[150:153], v[114:117]
	v_mfma_f32_16x16x32_bf16 v[102:105], v[182:185], v[158:161], v[102:105]
	v_mfma_f32_16x16x32_bf16 v[98:101], v[192:195], v[158:161], v[98:101]
	v_mfma_f32_16x16x32_bf16 v[86:89], v[182:185], v[166:169], v[86:89]
	v_mfma_f32_16x16x32_bf16 v[82:85], v[192:195], v[166:169], v[82:85]
	v_mfma_f32_16x16x32_bf16 v[70:73], v[182:185], v[174:177], v[70:73]
	v_mfma_f32_16x16x32_bf16 v[66:69], v[192:195], v[174:177], v[66:69]
	v_mfma_f32_16x16x32_bf16 v[118:121], v[186:189], v[154:157], v[118:121]
	v_mfma_f32_16x16x32_bf16 v[114:117], v[196:199], v[154:157], v[114:117]
	v_mfma_f32_16x16x32_bf16 v[102:105], v[186:189], v[162:165], v[102:105]
	v_mfma_f32_16x16x32_bf16 v[98:101], v[196:199], v[162:165], v[98:101]
	v_mfma_f32_16x16x32_bf16 v[86:89], v[186:189], v[170:173], v[86:89]
	v_mfma_f32_16x16x32_bf16 v[82:85], v[196:199], v[170:173], v[82:85]
	v_mfma_f32_16x16x32_bf16 v[70:73], v[186:189], v[178:181], v[70:73]
	v_mfma_f32_16x16x32_bf16 v[66:69], v[196:199], v[178:181], v[66:69]
	s_setprio 0
	s_mov_b32 m0, s63
	v_lshl_add_u64 v[202:203], s[14:15], 0, v[0:1]
	s_barrier
	ds_read_b128 v[150:153], v133 offset:16384
	ds_read_b128 v[154:157], v133 offset:17408
	ds_read_b128 v[158:161], v133 offset:18432
	ds_read_b128 v[162:165], v133 offset:19456
	ds_read_b128 v[166:169], v133 offset:20480
	ds_read_b128 v[170:173], v133 offset:21504
	ds_read_b128 v[174:177], v133 offset:22528
	ds_read_b128 v[178:181], v133 offset:23552
	global_load_lds_dwordx4 v[202:203], off
	v_lshl_add_u64 v[204:205], s[14:15], 0, v[130:131]
	s_mov_b32 m0, s18
	s_nop 0
	global_load_lds_dwordx4 v[204:205], off
	s_barrier
	s_waitcnt lgkmcnt(0)
	s_setprio 1
	s_waitcnt lgkmcnt(0)
	v_mfma_f32_16x16x32_bf16 v[62:65], v[134:137], v[150:153], v[62:65]
	v_mfma_f32_16x16x32_bf16 v[58:61], v[142:145], v[150:153], v[58:61]
	v_mfma_f32_16x16x32_bf16 v[46:49], v[134:137], v[158:161], v[46:49]
	v_mfma_f32_16x16x32_bf16 v[42:45], v[142:145], v[158:161], v[42:45]
	v_mfma_f32_16x16x32_bf16 v[30:33], v[134:137], v[166:169], v[30:33]
	v_mfma_f32_16x16x32_bf16 v[26:29], v[142:145], v[166:169], v[26:29]
	v_mfma_f32_16x16x32_bf16 v[14:17], v[134:137], v[174:177], v[14:17]
	v_mfma_f32_16x16x32_bf16 v[10:13], v[142:145], v[174:177], v[10:13]
	v_mfma_f32_16x16x32_bf16 v[62:65], v[138:141], v[154:157], v[62:65]
	v_mfma_f32_16x16x32_bf16 v[58:61], v[146:149], v[154:157], v[58:61]
	v_mfma_f32_16x16x32_bf16 v[46:49], v[138:141], v[162:165], v[46:49]
	v_mfma_f32_16x16x32_bf16 v[42:45], v[146:149], v[162:165], v[42:45]
	v_mfma_f32_16x16x32_bf16 v[30:33], v[138:141], v[170:173], v[30:33]
	v_mfma_f32_16x16x32_bf16 v[26:29], v[146:149], v[170:173], v[26:29]
	v_mfma_f32_16x16x32_bf16 v[14:17], v[138:141], v[178:181], v[14:17]
	v_mfma_f32_16x16x32_bf16 v[10:13], v[146:149], v[178:181], v[10:13]
	s_setprio 0
	s_barrier
	s_add_u32 s30, s6, 0x40000
	s_addc_u32 s31, s7, 0
	s_add_i32 s36, s36, s53
	v_lshl_add_u64 v[134:135], s[30:31], 0, v[0:1]
	s_mov_b32 m0, s36
	s_nop 0
	global_load_lds_dwordx4 v[134:135], off
	v_lshl_add_u64 v[134:135], s[30:31], 0, v[130:131]
	s_add_i32 m0, s36, 0x2000
	s_nop 0
	global_load_lds_dwordx4 v[134:135], off
	s_waitcnt vmcnt(6)
	s_barrier
	s_setprio 1
	v_mfma_f32_16x16x32_bf16 v[54:57], v[182:185], v[150:153], v[54:57]
	v_mfma_f32_16x16x32_bf16 v[50:53], v[192:195], v[150:153], v[50:53]
	v_mfma_f32_16x16x32_bf16 v[38:41], v[182:185], v[158:161], v[38:41]
	v_mfma_f32_16x16x32_bf16 v[34:37], v[192:195], v[158:161], v[34:37]
	v_mfma_f32_16x16x32_bf16 v[22:25], v[182:185], v[166:169], v[22:25]
	v_mfma_f32_16x16x32_bf16 v[18:21], v[192:195], v[166:169], v[18:21]
	v_mfma_f32_16x16x32_bf16 v[6:9], v[182:185], v[174:177], v[6:9]
	v_mfma_f32_16x16x32_bf16 v[2:5], v[192:195], v[174:177], v[2:5]
	v_mfma_f32_16x16x32_bf16 v[54:57], v[186:189], v[154:157], v[54:57]
	v_mfma_f32_16x16x32_bf16 v[50:53], v[196:199], v[154:157], v[50:53]
	v_mfma_f32_16x16x32_bf16 v[38:41], v[186:189], v[162:165], v[38:41]
	v_mfma_f32_16x16x32_bf16 v[34:37], v[196:199], v[162:165], v[34:37]
	v_mfma_f32_16x16x32_bf16 v[22:25], v[186:189], v[170:173], v[22:25]
	v_mfma_f32_16x16x32_bf16 v[18:21], v[196:199], v[170:173], v[18:21]
	v_mfma_f32_16x16x32_bf16 v[6:9], v[186:189], v[178:181], v[6:9]
	v_mfma_f32_16x16x32_bf16 v[2:5], v[196:199], v[178:181], v[2:5]
	s_setprio 0
	s_add_i32 s30, 0, 0x18000
	v_add_u32_e32 v146, s30, v132
	s_barrier
	ds_read_b128 v[134:137], v146
	ds_read_b128 v[138:141], v146 offset:1024
	ds_read_b128 v[142:145], v146 offset:2048
	ds_read_b128 v[146:149], v146 offset:3072
	s_add_u32 s14, s14, 0x40000
	s_addc_u32 s15, s15, 0
	s_mov_b32 m0, s19
	v_lshl_add_u64 v[182:183], s[14:15], 0, v[0:1]
	ds_read_b128 v[150:153], v133 offset:32768
	ds_read_b128 v[154:157], v133 offset:33792
	ds_read_b128 v[158:161], v133 offset:34816
	ds_read_b128 v[162:165], v133 offset:35840
	ds_read_b128 v[166:169], v133 offset:36864
	ds_read_b128 v[170:173], v133 offset:37888
	ds_read_b128 v[174:177], v133 offset:38912
	ds_read_b128 v[178:181], v133 offset:39936
	global_load_lds_dwordx4 v[182:183], off
	v_lshl_add_u64 v[182:183], s[14:15], 0, v[130:131]
	s_mov_b32 m0, s20
	s_nop 0
	global_load_lds_dwordx4 v[182:183], off
	s_waitcnt lgkmcnt(8)
	s_barrier
	s_waitcnt lgkmcnt(0)
	s_setprio 1
	s_waitcnt lgkmcnt(0)
	v_mfma_f32_16x16x32_bf16 v[126:129], v[134:137], v[150:153], v[126:129]
	v_mfma_f32_16x16x32_bf16 v[122:125], v[142:145], v[150:153], v[122:125]
	v_mfma_f32_16x16x32_bf16 v[110:113], v[134:137], v[158:161], v[110:113]
	v_mfma_f32_16x16x32_bf16 v[106:109], v[142:145], v[158:161], v[106:109]
	v_mfma_f32_16x16x32_bf16 v[94:97], v[134:137], v[166:169], v[94:97]
	v_mfma_f32_16x16x32_bf16 v[90:93], v[142:145], v[166:169], v[90:93]
	v_mfma_f32_16x16x32_bf16 v[78:81], v[134:137], v[174:177], v[78:81]
	v_mfma_f32_16x16x32_bf16 v[74:77], v[142:145], v[174:177], v[74:77]
	v_mfma_f32_16x16x32_bf16 v[126:129], v[138:141], v[154:157], v[126:129]
	v_mfma_f32_16x16x32_bf16 v[122:125], v[146:149], v[154:157], v[122:125]
	v_mfma_f32_16x16x32_bf16 v[110:113], v[138:141], v[162:165], v[110:113]
	v_mfma_f32_16x16x32_bf16 v[106:109], v[146:149], v[162:165], v[106:109]
	v_mfma_f32_16x16x32_bf16 v[94:97], v[138:141], v[170:173], v[94:97]
	v_mfma_f32_16x16x32_bf16 v[90:93], v[146:149], v[170:173], v[90:93]
	v_mfma_f32_16x16x32_bf16 v[78:81], v[138:141], v[178:181], v[78:81]
	v_mfma_f32_16x16x32_bf16 v[74:77], v[146:149], v[178:181], v[74:77]
	s_setprio 0
	s_barrier
	s_add_i32 s14, 0, 0x1c000
	s_add_i32 s15, s30, s53
	v_add_u32_e32 v196, s14, v132
	v_lshl_add_u64 v[190:191], v[190:191], 0, s[70:71]
	s_mov_b32 m0, s15
	ds_read_b128 v[182:185], v196
	ds_read_b128 v[186:189], v196 offset:1024
	ds_read_b128 v[192:195], v196 offset:2048
	ds_read_b128 v[196:199], v196 offset:3072
	global_load_lds_dwordx4 v[190:191], off
	v_lshl_add_u64 v[190:191], v[200:201], 0, s[70:71]
	s_add_i32 m0, s15, 0x2000
	s_nop 0
	global_load_lds_dwordx4 v[190:191], off
	s_barrier
	s_waitcnt lgkmcnt(0)
	s_setprio 1
	s_waitcnt lgkmcnt(0)
	v_mfma_f32_16x16x32_bf16 v[118:121], v[182:185], v[150:153], v[118:121]
	v_mfma_f32_16x16x32_bf16 v[114:117], v[192:195], v[150:153], v[114:117]
	v_mfma_f32_16x16x32_bf16 v[102:105], v[182:185], v[158:161], v[102:105]
	v_mfma_f32_16x16x32_bf16 v[98:101], v[192:195], v[158:161], v[98:101]
	v_mfma_f32_16x16x32_bf16 v[86:89], v[182:185], v[166:169], v[86:89]
	v_mfma_f32_16x16x32_bf16 v[82:85], v[192:195], v[166:169], v[82:85]
	v_mfma_f32_16x16x32_bf16 v[70:73], v[182:185], v[174:177], v[70:73]
	v_mfma_f32_16x16x32_bf16 v[66:69], v[192:195], v[174:177], v[66:69]
	v_mfma_f32_16x16x32_bf16 v[118:121], v[186:189], v[154:157], v[118:121]
	v_mfma_f32_16x16x32_bf16 v[114:117], v[196:199], v[154:157], v[114:117]
	v_mfma_f32_16x16x32_bf16 v[102:105], v[186:189], v[162:165], v[102:105]
	v_mfma_f32_16x16x32_bf16 v[98:101], v[196:199], v[162:165], v[98:101]
	v_mfma_f32_16x16x32_bf16 v[86:89], v[186:189], v[170:173], v[86:89]
	v_mfma_f32_16x16x32_bf16 v[82:85], v[196:199], v[170:173], v[82:85]
	v_mfma_f32_16x16x32_bf16 v[70:73], v[186:189], v[178:181], v[70:73]
	v_mfma_f32_16x16x32_bf16 v[66:69], v[196:199], v[178:181], v[66:69]
	s_setprio 0
	s_mov_b32 m0, s23
	v_lshl_add_u64 v[190:191], v[202:203], 0, s[70:71]
	s_barrier
	ds_read_b128 v[150:153], v133 offset:49152
	ds_read_b128 v[154:157], v133 offset:50176
	ds_read_b128 v[158:161], v133 offset:51200
	ds_read_b128 v[162:165], v133 offset:52224
	ds_read_b128 v[166:169], v133 offset:53248
	ds_read_b128 v[170:173], v133 offset:54272
	ds_read_b128 v[174:177], v133 offset:55296
	ds_read_b128 v[178:181], v133 offset:56320
	global_load_lds_dwordx4 v[190:191], off
	v_lshl_add_u64 v[190:191], v[204:205], 0, s[70:71]
	s_mov_b32 m0, s24
	s_nop 0
	global_load_lds_dwordx4 v[190:191], off
	s_barrier
	s_waitcnt lgkmcnt(0)
	s_setprio 1
	s_waitcnt lgkmcnt(0)
	v_mfma_f32_16x16x32_bf16 v[62:65], v[134:137], v[150:153], v[62:65]
	v_mfma_f32_16x16x32_bf16 v[58:61], v[142:145], v[150:153], v[58:61]
	v_mfma_f32_16x16x32_bf16 v[46:49], v[134:137], v[158:161], v[46:49]
	v_mfma_f32_16x16x32_bf16 v[42:45], v[142:145], v[158:161], v[42:45]
	v_mfma_f32_16x16x32_bf16 v[30:33], v[134:137], v[166:169], v[30:33]
	v_mfma_f32_16x16x32_bf16 v[26:29], v[142:145], v[166:169], v[26:29]
	v_mfma_f32_16x16x32_bf16 v[14:17], v[134:137], v[174:177], v[14:17]
	v_mfma_f32_16x16x32_bf16 v[10:13], v[142:145], v[174:177], v[10:13]
	v_mfma_f32_16x16x32_bf16 v[62:65], v[138:141], v[154:157], v[62:65]
	v_mfma_f32_16x16x32_bf16 v[58:61], v[146:149], v[154:157], v[58:61]
	v_mfma_f32_16x16x32_bf16 v[46:49], v[138:141], v[162:165], v[46:49]
	v_mfma_f32_16x16x32_bf16 v[42:45], v[146:149], v[162:165], v[42:45]
	v_mfma_f32_16x16x32_bf16 v[30:33], v[138:141], v[170:173], v[30:33]
	v_mfma_f32_16x16x32_bf16 v[26:29], v[146:149], v[170:173], v[26:29]
	v_mfma_f32_16x16x32_bf16 v[14:17], v[138:141], v[178:181], v[14:17]
	v_mfma_f32_16x16x32_bf16 v[10:13], v[146:149], v[178:181], v[10:13]
	s_setprio 0
	s_barrier
	s_add_u32 s6, s6, 0x40080
	s_addc_u32 s7, s7, 0
	s_add_i32 s14, s14, s53
	v_lshl_add_u64 v[134:135], s[6:7], 0, v[0:1]
	s_mov_b32 m0, s14
	s_nop 0
	global_load_lds_dwordx4 v[134:135], off
	v_lshl_add_u64 v[134:135], s[6:7], 0, v[130:131]
	s_add_i32 m0, s14, 0x2000
	s_nop 0
	global_load_lds_dwordx4 v[134:135], off
	s_waitcnt vmcnt(6)
	s_barrier
	s_setprio 1
	v_mfma_f32_16x16x32_bf16 v[54:57], v[182:185], v[150:153], v[54:57]
	v_mfma_f32_16x16x32_bf16 v[50:53], v[192:195], v[150:153], v[50:53]
	v_mfma_f32_16x16x32_bf16 v[38:41], v[182:185], v[158:161], v[38:41]
	v_mfma_f32_16x16x32_bf16 v[34:37], v[192:195], v[158:161], v[34:37]
	v_mfma_f32_16x16x32_bf16 v[22:25], v[182:185], v[166:169], v[22:25]
	v_mfma_f32_16x16x32_bf16 v[18:21], v[192:195], v[166:169], v[18:21]
	v_mfma_f32_16x16x32_bf16 v[6:9], v[182:185], v[174:177], v[6:9]
	v_mfma_f32_16x16x32_bf16 v[2:5], v[192:195], v[174:177], v[2:5]
	v_mfma_f32_16x16x32_bf16 v[54:57], v[186:189], v[154:157], v[54:57]
	v_mfma_f32_16x16x32_bf16 v[50:53], v[196:199], v[154:157], v[50:53]
	v_mfma_f32_16x16x32_bf16 v[38:41], v[186:189], v[162:165], v[38:41]
	v_mfma_f32_16x16x32_bf16 v[34:37], v[196:199], v[162:165], v[34:37]
	v_mfma_f32_16x16x32_bf16 v[22:25], v[186:189], v[170:173], v[22:25]
	v_mfma_f32_16x16x32_bf16 v[18:21], v[196:199], v[170:173], v[18:21]
	v_mfma_f32_16x16x32_bf16 v[6:9], v[186:189], v[178:181], v[6:9]
	v_mfma_f32_16x16x32_bf16 v[2:5], v[196:199], v[178:181], v[2:5]
	s_setprio 0
	s_add_i32 s29, s29, 2
	s_add_u32 s16, s16, 0x100
	s_addc_u32 s17, s17, 0
	s_add_u32 s4, s4, 0x100
	s_addc_u32 s5, s5, 0
	s_cmp_gt_u32 s29, 13
	s_barrier
	s_cbranch_scc0 .LBB0_44
	v_readlane_b32 s4, v253, 15
	v_mbcnt_lo_u32_b32 v0, -1, 0
	v_mbcnt_hi_u32_b32 v0, -1, v0
	s_ashr_i32 s29, s34, 1
	s_mov_b32 s30, s49
	v_add_u32_e32 v130, s4, v0
	s_mov_b32 s31, s48
	v_readlane_b32 s4, v252, 13
	v_readlane_b32 s5, v252, 14
	s_add_u32 s4, s31, s4
	s_addc_u32 s5, s30, s5
	v_ashrrev_i32_e32 v131, 31, v130
	v_lshl_add_u64 v[132:133], v[130:131], 4, s[4:5]
	s_mov_b64 s[4:5], 0x10480000
	v_lshl_add_u64 v[162:163], v[132:133], 0, s[4:5]
	s_lshl_b32 s4, s35, 8
	s_add_i32 s4, s4, s42
	s_bitcmp1_b32 s34, 0
	s_cselect_b64 s[14:15], -1, 0
	v_bfe_u32 v178, v0, 4, 2
	s_mov_b32 s6, s51
	s_mov_b32 s7, s50
	v_and_or_b32 v164, v0, 15, s4
	s_mov_b64 s[4:5], -1
	s_and_b64 vcc, exec, s[14:15]
	s_cbranch_vccz .LBB0_175
	global_load_dwordx4 v[158:161], v[162:163], off
	v_readlane_b32 s4, v252, 13
	v_readlane_b32 s5, v252, 14
	s_add_u32 s4, s7, s4
	s_addc_u32 s5, s6, s5
	s_cmp_gt_i32 s29, 0
	v_lshl_add_u64 v[166:167], v[130:131], 4, s[4:5]
	s_cselect_b64 s[6:7], -1, 0
	s_cmp_lt_i32 s29, 1
	s_cbranch_scc1 .LBB0_48
	global_load_dwordx4 v[142:145], v[166:167], off
